# layer-0 conversion by the hand routine too (GU2/D2 of every layer now in the phase-1 idle slot)
# speedup vs baseline: 1.0435x; 1.0040x over previous
; __device__ __forceinline__ CvtDesc cvt_decode(CArgs a, int layer, int it) {
;     unsigned char* wsw = a->ws + WS_W;
;     constexpr int I_GU = 16 * 176, I_D = 44 * 32, I_IN = 16 * 144, I_UQ = 4 * 24, I_UKV = 2 * 32;
;     CvtDesc d;
;     int r = it;
;     if (r < 2 * I_GU) {
;         const int which = r / I_GU; r -= which * I_GU;
;         const int db = r % 176, kb = r / 176, tile = db >> 3, sub = db & 7;
;         const float* Wg = (which ? a->ffn2_wg : a->ffn1_wg) + (size_t)layer * DM * FF; const float* Wu = (which ? a->ffn2_wu : a->ffn1_wu) + (size_t)layer * DM * FF;
;         d.W = sub < 4 ? Wg : Wu; d.gain = (which ? a->ffn2_norm : a->ffn1_norm) + layer * DM; d.WT = (bf16_t*)(wsw + (which ? W_GU2 : W_GU1));
;         d.N = FF; d.K = DM; d.ld = DM; d.srccol = tile * 128 + (sub & 3) * 32; d.destrow = db * 32; d.k0 = kb * 64; return d;
;     }
;     r -= 2 * I_GU;
;     if (r < 2 * I_D) {
;         const int which = r / I_D; r -= which * I_D;
;         const int db = r % 32, kb = r / 32;
;         d.W = (which ? a->ffn2_wd : a->ffn1_wd) + (size_t)layer * FF * DM; d.gain = nullptr; d.WT = (bf16_t*)(wsw + (which ? W_D2 : W_D1));
;         d.N = DM; d.K = FF; d.ld = HLD; d.srccol = db * 32; d.destrow = db * 32; d.k0 = kb * 64; return d;
;     }
;     r -= 2 * I_D;
;     if (r < I_IN) {
;         const int db = r % 144, kb = r / 144, uc = db * 32;
;         int oc;
;         if (uc < 2560) oc = uc; else if (uc < 2816) oc = 2592 + (uc - 2560); else if (uc < 2944) oc = 2848 + (uc - 2816); else if (uc < 2976) oc = 2976 + (uc - 2944);
; __device__ __forceinline__ void phase_convert(CArgs a, int layer, LAS unsigned char* lds, int G) {
;     const unsigned char* WSB = a->ws;
;     const int tid = ltid(), lane = tid & 63, wave = tid >> 6;
;     LAS float* scr = (LAS float*)(lds + wave * 16384);
;     const int gw = lbid() * NWAVES + wave, NGW = G * NWAVES;
;     constexpr int NIT = 2 * 16 * 176 + 2 * 44 * 32 + 16 * 144 + 4 * 24 + 2 * 32 + 32 * 32;
;     {
;         int it = gw;
;         float wv[32]; CvtDesc cur;
;         if (it < NIT) { cur = cvt_decode(a, layer, it); cvt_load(cur, wv, lane); }
; #pragma unroll 1
;         while (it < NIT) {
;             const int nxt = it + NGW;
;             float wn[32]; CvtDesc nd = cur;
;             if (nxt < NIT) { nd = cvt_decode(a, layer, nxt); cvt_load(nd, wn, lane); }
.LBB0_377:
	s_cmp_lg_u32 s9, 0
	s_cbranch_scc1 .LBB0_496
	s_branch .Lmcv_l0
	s_load_dwordx2 s[10:11], s[6:7], 0xe8
	v_mov_b32_e32 v51, v244
	v_readlane_b32 s92, v253, 0
	s_waitcnt lgkmcnt(0)
	s_add_u32 s12, s10, 0x600000
	s_addc_u32 s13, s11, 0
	s_ashr_i32 s9, s8, 31
	s_lshl_b32 s2, s8, 9
	s_lshl_b32 s16, s8, 10
	s_lshl_b64 s[14:15], s[8:9], 23
	v_writelane_b32 v255, s14, 12
	s_ashr_i32 s3, s2, 31
	s_ashr_i32 s17, s16, 31
	v_writelane_b32 v255, s15, 13
	s_add_u32 s20, s10, 0x22a0000
	v_writelane_b32 v255, s2, 14
	s_addc_u32 s21, s11, 0
	s_lshl_b32 s24, s8, 7
	v_writelane_b32 v255, s3, 15
	s_lshl_b64 s[2:3], s[8:9], 19
	s_ashr_i32 s25, s24, 31
	s_add_u32 s22, s10, 0x2260000
	s_addc_u32 s23, s11, 0
	s_lshl_b32 s14, s8, 8
	s_ashr_i32 s15, s14, 31
	v_writelane_b32 v255, s2, 16
	s_add_u32 s48, s10, 0x2200000
	s_addc_u32 s49, s11, 0
	v_writelane_b32 v255, s3, 17
	s_mul_hi_i32 s2, s8, 0xc0000
	v_writelane_b32 v255, s2, 18
	s_mul_i32 s2, s8, 0xc0000
	s_add_u32 s50, s10, 0x1900000
	v_writelane_b32 v255, s2, 20
	s_mul_hi_i32 s2, s8, 0x11c0000
	s_addc_u32 s51, s11, 0
	v_ashrrev_i32_e32 v8, 6, v51
	s_lshl_b32 s93, s92, 3
	v_writelane_b32 v255, s2, 10
	v_add_u32_e32 v42, s93, v8
	s_movk_i32 s2, 0x2ea0
	s_mul_i32 s34, s8, 0x11c0000
	s_mul_hi_i32 s9, s8, 0xb00000
	s_mul_i32 s8, s8, 0xb00000
	v_and_b32_e32 v58, 63, v51
	v_cmp_gt_i32_e32 vcc, s2, v42
	s_and_saveexec_b64 s[54:55], vcc
	s_cbranch_execz .LBB0_429
	s_movk_i32 s2, 0x15ff
	v_cmp_lt_i32_e64 s[40:41], s2, v42
	s_and_saveexec_b64 s[2:3], s[40:41]
	s_xor_b64 s[58:59], exec, s[2:3]
	s_cbranch_execz .LBB0_424
	s_movk_i32 s2, 0x20ff
	v_cmp_lt_u32_e64 s[40:41], s2, v42
	s_and_saveexec_b64 s[2:3], s[40:41]
	s_xor_b64 s[26:27], exec, s[2:3]
	s_cbranch_execz .LBB0_421
	s_movk_i32 s2, 0x29ff
	v_cmp_lt_u32_e64 s[40:41], s2, v42
	s_and_saveexec_b64 s[2:3], s[40:41]
	s_xor_b64 s[28:29], exec, s[2:3]
	s_cbranch_execz .LBB0_400
	s_movk_i32 s2, 0x2a5f
	v_cmp_lt_u32_e64 s[40:41], s2, v42
	s_and_saveexec_b64 s[2:3], s[40:41]
	s_xor_b64 s[60:61], exec, s[2:3]
	s_cbranch_execz .LBB0_397
	s_movk_i32 s2, 0x2a9f
	v_cmp_lt_u32_e64 s[40:41], s2, v42
	v_lshlrev_b32_e32 v0, 1, v42
	s_and_saveexec_b64 s[2:3], s[40:41]
	s_xor_b64 s[42:43], exec, s[2:3]
	s_cbranch_execz .LBB0_393
	s_load_dwordx2 s[36:37], s[6:7], 0xb8
	v_and_b32_e32 v0, 0x7fffffc0, v0
	v_add_u32_e32 v44, 0xffffaac0, v0
	s_movk_i32 s2, 0x3ff
	v_cmp_lt_u32_e64 s[40:41], s2, v44
	s_and_saveexec_b64 s[2:3], s[40:41]
	s_xor_b64 s[88:89], exec, s[2:3]
	s_cbranch_execz .LBB0_390
	s_movk_i32 s2, 0x5ff
	v_cmp_lt_u32_e64 s[40:41], s2, v44
	s_and_saveexec_b64 s[2:3], s[40:41]
	s_xor_b64 s[2:3], exec, s[2:3]
	s_cbranch_execz .LBB0_387
	s_load_dwordx2 s[18:19], s[6:7], 0xb0
	v_readlane_b32 s40, v255, 14
	v_readlane_b32 s41, v255, 15
	s_lshl_b64 s[40:41], s[40:41], 2
	s_waitcnt lgkmcnt(0)
	s_add_u32 s18, s18, s40
	s_addc_u32 s19, s19, s41
	s_add_u32 s90, s18, 0xffffe800
	s_addc_u32 s91, s19, -1

; __device__ __forceinline__ int ltid() { int t = threadIdx.x; asm volatile("" : "+v"(t)); return t; }
; __device__ __forceinline__ int lbid() { int t = blockIdx.x; asm volatile("" : "+s"(t)); return t; }
; #define LAS __attribute__((address_space(3)))
; __device__ __forceinline__ CArgs get_args() { CArgs p = (CArgs)__builtin_amdgcn_kernarg_segment_ptr(); asm volatile("" : "+s"(p)); return p; }
; __device__ __forceinline__ void phase_convert(CArgs a, int layer, LAS unsigned char* lds, int G) {
;     const unsigned char* WSB = a->ws;
;     const int tid = ltid(), lane = tid & 63, wave = tid >> 6;
;     LAS float* scr = (LAS float*)(lds + wave * 16384);
;     const int gw = lbid() * NWAVES + wave, NGW = G * NWAVES;
;     constexpr int NIT = 2 * 16 * 176 + 2 * 44 * 32 + 16 * 144 + 4 * 24 + 2 * 32 + 32 * 32;
;     {
;         int it = gw;
;         float wv[32]; CvtDesc cur;
;         if (it < NIT) { cur = cvt_decode(a, layer, it); cvt_load(cur, wv, lane); }
; __global__ void __launch_bounds__(NTHR, 2) mk_fwd(Args a_by_value) {
;     ...
;     for (int ph = ph_lo; ph < ph_hi; ++ph) {
;         CArgs a = get_args(); const int bid = lbid();
;         const int layer = ph / PH_PER_LAYER, k = ph % PH_PER_LAYER;
;         if (PH_EN(0) && k == 0) {
;             for (int rep = 0; rep < REP_CV; ++rep) phase_convert(a, layer, lds, G);
;         } else if (PH_EN(1) && (k == 1 || k == 7)) {
;             pg8::Gemm g{XB, (const bf16_t*)(wsw + (k == 1 ? W_GU1 : W_GU2)), T, 2 * FF, DM, XLD, DM}; pg8::StaticOrder S; S.init(T, 2 * FF, G, bid);
;             EpiSwiglu E{ws, Hb, rowss};
;             for (int rep = 0; rep < REP_GU; ++rep) pg8::gemm_phase<EpiSwiglu, pg8::StaticOrder, true>(lds, g, S, E);
.Lmcv_entry:
	v_readlane_b32 s2, v253, 1
	v_readlane_b32 s16, v253, 0
	s_nop 3
	s_mul_hi_i32 s3, s2, 0x38e38e39
	s_lshr_b32 s10, s3, 31
	s_ashr_i32 s3, s3, 1
	s_add_i32 s3, s3, s10
	s_mul_i32 s10, s3, 9
	s_sub_i32 s2, s2, s10
	s_lshr_b32 s17, s64, 1
	s_cmp_lt_u32 s16, s17
	s_cbranch_scc1 .Lmcv_exit
	s_cmp_eq_u32 s2, 1
	s_cbranch_scc0 .Lmcv_k37
	s_mov_b32 s13, 1
	s_mov_b32 s29, s3
	s_movk_i32 s12, 0x1080
	s_branch .Lmcv_go

; __device__ __forceinline__ int ltid() { int t = threadIdx.x; asm volatile("" : "+v"(t)); return t; }
; __device__ __forceinline__ int lbid() { int t = blockIdx.x; asm volatile("" : "+s"(t)); return t; }
; #define LAS __attribute__((address_space(3)))
; __device__ __forceinline__ CvtDesc cvt_decode(CArgs a, int layer, int it) {
;     ...
;     if (r < 2 * I_GU) {
;         const int which = r / I_GU; r -= which * I_GU;
;         const int db = r % 176, kb = r / 176, tile = db >> 3, sub = db & 7;
;         const float* Wg = (which ? a->ffn2_wg : a->ffn1_wg) + (size_t)layer * DM * FF; const float* Wu = (which ? a->ffn2_wu : a->ffn1_wu) + (size_t)layer * DM * FF;
;         d.W = sub < 4 ? Wg : Wu; d.gain = (which ? a->ffn2_norm : a->ffn1_norm) + layer * DM; d.WT = (bf16_t*)(wsw + (which ? W_GU2 : W_GU1));
;         d.N = FF; d.K = DM; d.ld = DM; d.srccol = tile * 128 + (sub & 3) * 32; d.destrow = db * 32; d.k0 = kb * 64; return d;
; __device__ __forceinline__ void phase_convert(CArgs a, int layer, LAS unsigned char* lds, int G) {
;     const unsigned char* WSB = a->ws;
;     const int tid = ltid(), lane = tid & 63, wave = tid >> 6;
;     LAS float* scr = (LAS float*)(lds + wave * 16384);
;     const int gw = lbid() * NWAVES + wave, NGW = G * NWAVES;
;     constexpr int NIT = 2 * 16 * 176 + 2 * 44 * 32 + 16 * 144 + 4 * 24 + 2 * 32 + 32 * 32;
;     {
;         int it = gw;
;         float wv[32]; CvtDesc cur;
;         if (it < NIT) { cur = cvt_decode(a, layer, it); cvt_load(cur, wv, lane); }
; #pragma unroll 1
;         while (it < NIT) {
;             const int nxt = it + NGW;
;             float wn[32]; CvtDesc nd = cur;
;             if (nxt < NIT) { nd = cvt_decode(a, layer, nxt); cvt_load(nd, wn, lane); }
.Lmcv_go:
	s_load_dwordx2 s[88:89], s[6:7], 0xe8
	v_readfirstlane_b32 s2, v244
	v_and_b32_e32 v2, 63, v244
	v_lshrrev_b32_e32 v3, 5, v2
	v_and_b32_e32 v4, 31, v2
	v_lshlrev_b32_e32 v4, 2, v4
	s_lshr_b32 s2, s2, 6
	s_lshl_b32 s3, s2, 14
	v_mul_u32_u24_e32 v5, 0x84, v3
	v_add3_u32 v5, v5, v4, s3
	v_and_b32_e32 v7, 7, v2
	v_lshrrev_b32_e32 v8, 3, v2
	v_mul_u32_u24_e32 v6, 0x420, v7
	v_lshl_add_u32 v6, v8, 2, v6
	v_add_u32_e32 v6, s3, v6
	v_lshlrev_b32_e32 v9, 4, v7
	v_lshlrev_b32_e32 v7, 5, v7
	s_waitcnt lgkmcnt(0)
	s_and_b32 s89, s89, 0xffff
	s_mov_b32 s90, s62
	s_mov_b32 s91, s63
	s_lshr_b32 s17, s64, 1
	s_sub_u32 s16, s16, s17
	s_lshl_b32 s16, s16, 3
	s_add_u32 s10, s16, s2
	s_sub_u32 s11, s64, s17
	s_lshl_b32 s11, s11, 3
	s_cmp_lt_u32 s10, s12
	s_cbranch_scc0 .Lmcv_rd_s
	s_mov_b32 s20, 1
	s_cmp_eq_u32 s13, 2
	s_cbranch_scc1 .Lmcv_t2_1
	s_cmpk_lt_u32 s10, 0xb00
	s_cbranch_scc0 .Lmcv_d_1
	s_mul_hi_u32 s2, s10, 0x1745d18
	s_mul_i32 s3, s2, 0xb0
	s_sub_u32 s3, s10, s3
	s_lshr_b32 s48, s3, 3
	s_and_b32 s49, s3, 3
	s_lshl_b32 s50, s48, 7
	s_lshl_b32 s49, s49, 5
	s_add_u32 s50, s50, s49
	s_lshl_b32 s51, s3, 5
	s_lshl_b32 s2, s2, 6
	s_bfe_u32 s3, s3, 0x10002
	s_lshl_b32 s3, s3, 3
	s_cmp_eq_u32 s13, 1
	s_cselect_b32 s17, 0xc8, 24
	s_add_u32 s17, s17, s3
	s_cmp_eq_u32 s13, 1
	s_cselect_b32 s48, 0xc0, 16
	s_mov_b32 s21, 0x600000
	s_cselect_b32 s21, 0x26a0000, s21
	s_mov_b32 s18, 0xb00000
	s_lshl_b32 s49, s29, 12
	s_movk_i32 s23, 0x2c00
	s_movk_i32 s22, 0x800
	s_branch .Lmcv_com_1

; __device__ __forceinline__ int ltid() { int t = threadIdx.x; asm volatile("" : "+v"(t)); return t; }
; __device__ __forceinline__ int lbid() { int t = blockIdx.x; asm volatile("" : "+s"(t)); return t; }
; #define LAS __attribute__((address_space(3)))
; __device__ __forceinline__ CvtDesc cvt_decode(CArgs a, int layer, int it) {
;     ...
;     if (r < 2 * I_GU) {
;         const int which = r / I_GU; r -= which * I_GU;
;         const int db = r % 176, kb = r / 176, tile = db >> 3, sub = db & 7;
;         const float* Wg = (which ? a->ffn2_wg : a->ffn1_wg) + (size_t)layer * DM * FF; const float* Wu = (which ? a->ffn2_wu : a->ffn1_wu) + (size_t)layer * DM * FF;
;         d.W = sub < 4 ? Wg : Wu; d.gain = (which ? a->ffn2_norm : a->ffn1_norm) + layer * DM; d.WT = (bf16_t*)(wsw + (which ? W_GU2 : W_GU1));
;         d.N = FF; d.K = DM; d.ld = DM; d.srccol = tile * 128 + (sub & 3) * 32; d.destrow = db * 32; d.k0 = kb * 64; return d;
;     }
;     r -= 2 * I_GU;
;     if (r < 2 * I_D) {
;         const int which = r / I_D; r -= which * I_D;
;         const int db = r % 32, kb = r / 32;
;         d.W = (which ? a->ffn2_wd : a->ffn1_wd) + (size_t)layer * FF * DM; d.gain = nullptr; d.WT = (bf16_t*)(wsw + (which ? W_D2 : W_D1));
;         d.N = DM; d.K = FF; d.ld = HLD; d.srccol = db * 32; d.destrow = db * 32; d.k0 = kb * 64; return d;
;     }
; __device__ __forceinline__ void phase_convert(CArgs a, int layer, LAS unsigned char* lds, int G) {
;     const unsigned char* WSB = a->ws;
;     const int tid = ltid(), lane = tid & 63, wave = tid >> 6;
;     LAS float* scr = (LAS float*)(lds + wave * 16384);
;     const int gw = lbid() * NWAVES + wave, NGW = G * NWAVES;
;     constexpr int NIT = 2 * 16 * 176 + 2 * 44 * 32 + 16 * 144 + 4 * 24 + 2 * 32 + 32 * 32;
;     {
;         int it = gw;
;         float wv[32]; CvtDesc cur;
;         if (it < NIT) { cur = cvt_decode(a, layer, it); cvt_load(cur, wv, lane); }
; #pragma unroll 1
;         while (it < NIT) {
;             const int nxt = it + NGW;
;             float wn[32]; CvtDesc nd = cur;
;             if (nxt < NIT) { nd = cvt_decode(a, layer, nxt); cvt_load(nd, wn, lane); }
.Lmcv_l0:
	v_readlane_b32 s16, v253, 0
	s_mov_b32 s29, 0
	s_load_dwordx2 s[88:89], s[6:7], 0xe8
	v_readfirstlane_b32 s2, v244
	v_and_b32_e32 v2, 63, v244
	v_lshrrev_b32_e32 v3, 5, v2
	v_and_b32_e32 v4, 31, v2
	v_lshlrev_b32_e32 v4, 2, v4
	s_lshr_b32 s2, s2, 6
	s_lshl_b32 s3, s2, 14
	v_mul_u32_u24_e32 v5, 0x84, v3
	v_add3_u32 v5, v5, v4, s3
	v_and_b32_e32 v7, 7, v2
	v_lshrrev_b32_e32 v8, 3, v2
	v_mul_u32_u24_e32 v6, 0x420, v7
	v_lshl_add_u32 v6, v8, 2, v6
	v_add_u32_e32 v6, s3, v6
	v_lshlrev_b32_e32 v9, 4, v7
	v_lshlrev_b32_e32 v7, 5, v7
	s_waitcnt lgkmcnt(0)
	s_and_b32 s89, s89, 0xffff
	s_mov_b32 s90, s62
	s_mov_b32 s91, s63
	s_lshl_b32 s16, s16, 3
	s_add_u32 s27, s16, s2
	s_lshl_b32 s11, s64, 3
	s_mov_b32 s13, 0
	s_movk_i32 s12, 0x1080
	s_mov_b32 s10, s27
	s_cmp_lt_u32 s10, s12
	s_cbranch_scc0 .Lmcv_rd_l0
	s_mov_b32 s20, 1
	s_cmp_eq_u32 s13, 2
	s_cbranch_scc1 .Lmcv_t2_6
	s_cmpk_lt_u32 s10, 0xb00
	s_cbranch_scc0 .Lmcv_d_6
	s_mul_hi_u32 s2, s10, 0x1745d18
	s_mul_i32 s3, s2, 0xb0
	s_sub_u32 s3, s10, s3
	s_lshr_b32 s48, s3, 3
	s_and_b32 s49, s3, 3
	s_lshl_b32 s50, s48, 7
	s_lshl_b32 s49, s49, 5
	s_add_u32 s50, s50, s49
	s_lshl_b32 s51, s3, 5
	s_lshl_b32 s2, s2, 6
	s_bfe_u32 s3, s3, 0x10002
	s_lshl_b32 s3, s3, 3
	s_cmp_eq_u32 s13, 1
	s_cselect_b32 s17, 0xc8, 24
	s_add_u32 s17, s17, s3
	s_cmp_eq_u32 s13, 1
	s_cselect_b32 s48, 0xc0, 16
	s_mov_b32 s21, 0x600000
	s_cselect_b32 s21, 0x26a0000, s21
	s_mov_b32 s18, 0xb00000
	s_lshl_b32 s49, s29, 12
	s_movk_i32 s23, 0x2c00
	s_movk_i32 s22, 0x800
	s_branch .Lmcv_com_6

; __device__ __forceinline__ CvtDesc cvt_decode(CArgs a, int layer, int it) {
;     ...
;     r -= 2 * I_D;
;     if (r < I_IN) {
;         const int db = r % 144, kb = r / 144, uc = db * 32;
;         int oc;
;         if (uc < 2560) oc = uc; else if (uc < 2816) oc = 2592 + (uc - 2560); else if (uc < 2944) oc = 2848 + (uc - 2816); else if (uc < 2976) oc = 2976 + (uc - 2944);
;         else if (uc < 3008) oc = 2560 + (uc - 2976); else if (uc < 3072) oc = -1; else oc = 3008 + (uc - 3072);
;         d.W = oc >= 0 ? a->w_in + (size_t)layer * DM * DIN : nullptr; d.gain = a->mix_norm + layer * DM; d.WT = (bf16_t*)(wsw + W_IN);
;         d.N = DIN; d.K = DM; d.ld = DM; d.srccol = oc; d.destrow = uc; d.k0 = kb * 64; return d;
;     }
;     r -= I_IN;
;     if (r < I_UQ) {
;         const int db = r % 24, kb = r / 24;
;         d.W = a->mla_w_uq + (size_t)layer * 256 * 768; d.gain = a->mla_q_norm + layer * 256; d.WT = (bf16_t*)(wsw + W_UQ);
;         d.N = 768; d.K = 256; d.ld = 256; d.srccol = db * 32; d.destrow = db * 32; d.k0 = kb * 64; return d;
;     }
;     r -= I_UQ;
;     if (r < I_UKV) {
;         const int db = r % 32, kb = r / 32, pn = db >> 3, bj = (db & 7) >> 2, wc = db & 3;
;         d.W = a->mla_w_ukv + (size_t)layer * 128 * 1024; d.gain = a->mla_kv_norm + layer * 128; d.WT = (bf16_t*)(wsw + W_UKV);
;         d.N = 1024; d.K = 128; d.ld = 128; d.srccol = (pn < 2) ? (4 * pn + wc) * 128 + 32 * bj : (4 * (pn - 2) + wc) * 128 + 64 + 32 * bj; d.destrow = db * 32; d.k0 = kb * 64; return d;
;     }
;     r -= I_UKV;
;     {
;         const int db = r % 32, kb = r / 32, k0 = kb * 64;
;         d.W = a->w_out + (size_t)layer * 2048 * DM;
;         d.gain = (k0 < 1024) ? a->ssd_norm + layer * 1024 : (k0 < 1536) ? a->mla_out_norm + layer * 512 - 1024 : a->conv_out_norm + layer * 512 - 1536;
;         d.WT = (bf16_t*)(wsw + W_OUT); d.N = DM; d.K = 2048; d.ld = 2048; d.srccol = db * 32; d.destrow = db * 32; d.k0 = k0; return d;
;     }
.Lmcv_rd_l0:
	s_waitcnt vmcnt(0)
	s_mov_b32 s13, 2
	s_movk_i32 s12, 0xda0
	s_mov_b32 s10, s27
	s_cmp_lt_u32 s10, s12
	s_cbranch_scc0 .Lmcv_rd_l2
	s_mov_b32 s20, 1
	s_cmp_eq_u32 s13, 2
	s_cbranch_scc1 .Lmcv_t2_11
	s_cmpk_lt_u32 s10, 0xb00
	s_cbranch_scc0 .Lmcv_d_11
	s_mul_hi_u32 s2, s10, 0x1745d18
	s_mul_i32 s3, s2, 0xb0
	s_sub_u32 s3, s10, s3
	s_lshr_b32 s48, s3, 3
	s_and_b32 s49, s3, 3
	s_lshl_b32 s50, s48, 7
	s_lshl_b32 s49, s49, 5
	s_add_u32 s50, s50, s49
	s_lshl_b32 s51, s3, 5
	s_lshl_b32 s2, s2, 6
	s_bfe_u32 s3, s3, 0x10002
	s_lshl_b32 s3, s3, 3
	s_cmp_eq_u32 s13, 1
	s_cselect_b32 s17, 0xc8, 24
	s_add_u32 s17, s17, s3
	s_cmp_eq_u32 s13, 1
	s_cselect_b32 s48, 0xc0, 16
	s_mov_b32 s21, 0x600000
	s_cselect_b32 s21, 0x26a0000, s21
	s_mov_b32 s18, 0xb00000
	s_lshl_b32 s49, s29, 12
	s_movk_i32 s23, 0x2c00
	s_movk_i32 s22, 0x800
	s_branch .Lmcv_com_11

; __device__ __forceinline__ int lbid() { int t = blockIdx.x; asm volatile("" : "+s"(t)); return t; }
; __device__ __forceinline__ unsigned cvt_pk_bf16(float lo, float hi) { f32x2_t v = {lo, hi}; bf16x2_t b = __builtin_convertvector(v, bf16x2_t); return __builtin_bit_cast(unsigned, b); }
; __device__ __forceinline__ void wt8(void* p, unsigned lo, unsigned hi) { __hip_atomic_store((u64_t*)p, (u64_t)lo | ((u64_t)hi << 32), __ATOMIC_RELAXED, __HIP_MEMORY_SCOPE_AGENT); }
; __device__ __forceinline__ void wt4f(float* p, float v) { __hip_atomic_store(p, v, __ATOMIC_RELAXED, __HIP_MEMORY_SCOPE_AGENT); }
; __device__ __forceinline__ void phase_convert(CArgs a, int layer, LAS unsigned char* lds, int G) {
;     ...
;     if (layer == 0) {
;         float* ctl = (float*)(a->ws + WS_CTL + CTL_ROWSS);
;         bf16_t* xb = (bf16_t*)(a->ws + WS_XB);
;         for (int m = gw; m < T; m += NGW) {
;             const f32x4* xr = (const f32x4*)(a->x + (size_t)m * DM) + lane; float s = 0.f;
; #pragma unroll
;             for (int j = 0; j < 4; ++j) { const f32x4 v = xr[64 * j]; s += (v[0] * v[0] + v[1] * v[1]) + (v[2] * v[2] + v[3] * v[3]);
;                 u32x2 w; w.x = cvt_pk_bf16(v[0], v[1]); w.y = cvt_pk_bf16(v[2], v[3]); wt8(xb + (size_t)m * XLD + 256 * j + 4 * lane, w.x, w.y); }
;             s = wave_sum(s);
;             if (lane < 16) wt4f(ctl + (size_t)m * 16 + lane, (lane == 0) ? s : 0.f);
;         }
;         float2* cst = (float2*)(a->ws + WS_CS);
;         for (int i = lbid() * NTHR + tid; i < T * 16; i += G * NTHR) {
.Lmcv_rd_l2:
	s_waitcnt vmcnt(0)
	s_load_dwordx2 s[10:11], s[6:7], 0xe8
	s_mov_b64 s[42:43], -1
	v_mov_b32_e32 v51, v244
	v_and_b32_e32 v58, 63, v244
	v_lshrrev_b32_e32 v42, 6, v244
	v_readlane_b32 s2, v253, 0
	s_nop 3
	s_lshl_b32 s2, s2, 3
	v_add_u32_e32 v42, s2, v42
	s_waitcnt lgkmcnt(0)
	s_branch .LBB0_486
